# GEMM epilogues of in-proj, MLP2 and out-proj store 16-byte dwordx4 (lane pairs exchange packed bf16 pieces with v_permlane16_swap) instead of 8-byte dwordx2: half the store instructions, 64-byte runs
# speedup vs baseline: 1.0282x; 1.0140x over previous
.Lpfa_skip_ip:
	s_mov_b32 s99, 1
	v_or_b32_e32 v1, s25, v238
	v_and_b32_e32 v0, 0xc0, v203
	v_add_u32_e32 v8, v1, v239
	v_lshlrev_b32_e32 v1, 2, v201
	v_or3_b32 v6, v1, v0, s34
	v_mov_b64_e32 v[0:1], s[30:31]
	v_mad_i64_i32 v[2:3], s[10:11], v8, s33, v[0:1]
	v_lshlrev_b32_e32 v6, 1, v6
	v_and_b32_e32 v9, 1, v201
	v_mul_u32_u24_e32 v9, 24, v9
	v_add_u32_e32 v6, v6, v9
	v_mov_b32_e32 v7, v17
	v_cvt_pk_bf16_f32 v10, v158, v159
	v_cvt_pk_bf16_f32 v11, v160, v161
	v_cvt_pk_bf16_f32 v12, v154, v155
	v_cvt_pk_bf16_f32 v13, v156, v157
	v_cvt_pk_bf16_f32 v162, v150, v151
	v_cvt_pk_bf16_f32 v163, v152, v153
	v_cvt_pk_bf16_f32 v164, v146, v147
	v_cvt_pk_bf16_f32 v165, v148, v149
	v_lshl_add_u64 v[2:3], v[2:3], 0, v[6:7]
	s_nop 1
	v_permlane16_swap_b32 v10, v12
	v_permlane16_swap_b32 v11, v13
	v_permlane16_swap_b32 v162, v164
	v_permlane16_swap_b32 v163, v165
	s_nop 1
	global_store_dwordx4 v[2:3], v[10:13], off
	global_store_dwordx4 v[2:3], v[162:165], off offset:64
	v_cvt_pk_bf16_f32 v166, v142, v143
	v_cvt_pk_bf16_f32 v167, v144, v145
	v_cvt_pk_bf16_f32 v168, v138, v139
	v_cvt_pk_bf16_f32 v169, v140, v141
	v_cvt_pk_bf16_f32 v170, v134, v135
	v_cvt_pk_bf16_f32 v171, v136, v137
	v_cvt_pk_bf16_f32 v172, v130, v131
	v_cvt_pk_bf16_f32 v173, v132, v133
	v_or_b32_e32 v2, 16, v8
	v_mad_i64_i32 v[2:3], s[10:11], v2, s33, v[0:1]
	v_lshl_add_u64 v[2:3], v[2:3], 0, v[6:7]
	s_nop 1
	v_permlane16_swap_b32 v166, v168
	v_permlane16_swap_b32 v167, v169
	v_permlane16_swap_b32 v170, v172
	v_permlane16_swap_b32 v171, v173
	s_nop 1
	global_store_dwordx4 v[2:3], v[166:169], off
	global_store_dwordx4 v[2:3], v[170:173], off offset:64
	v_cvt_pk_bf16_f32 v10, v126, v127
	v_cvt_pk_bf16_f32 v11, v128, v129
	v_cvt_pk_bf16_f32 v12, v122, v123
	v_cvt_pk_bf16_f32 v13, v124, v125
	v_cvt_pk_bf16_f32 v162, v118, v119
	v_cvt_pk_bf16_f32 v163, v120, v121
	v_cvt_pk_bf16_f32 v164, v114, v115
	v_cvt_pk_bf16_f32 v165, v116, v117
	v_or_b32_e32 v2, 32, v8
	v_mad_i64_i32 v[2:3], s[10:11], v2, s33, v[0:1]
	v_lshl_add_u64 v[2:3], v[2:3], 0, v[6:7]
	s_nop 1
	v_permlane16_swap_b32 v10, v12
	v_permlane16_swap_b32 v11, v13
	v_permlane16_swap_b32 v162, v164
	v_permlane16_swap_b32 v163, v165
	s_nop 1
	global_store_dwordx4 v[2:3], v[10:13], off
	global_store_dwordx4 v[2:3], v[162:165], off offset:64
	v_cvt_pk_bf16_f32 v166, v110, v111
	v_cvt_pk_bf16_f32 v167, v112, v113
	v_cvt_pk_bf16_f32 v168, v106, v107
	v_cvt_pk_bf16_f32 v169, v108, v109
	v_cvt_pk_bf16_f32 v170, v102, v103
	v_cvt_pk_bf16_f32 v171, v104, v105
	v_cvt_pk_bf16_f32 v172, v86, v87
	v_cvt_pk_bf16_f32 v173, v88, v89
	v_or_b32_e32 v2, 48, v8
	v_mad_i64_i32 v[2:3], s[10:11], v2, s33, v[0:1]
	v_lshl_add_u64 v[2:3], v[2:3], 0, v[6:7]
	s_nop 1
	v_permlane16_swap_b32 v166, v168
	v_permlane16_swap_b32 v167, v169
	v_permlane16_swap_b32 v170, v172
	v_permlane16_swap_b32 v171, v173
	s_nop 1
	global_store_dwordx4 v[2:3], v[166:169], off
	global_store_dwordx4 v[2:3], v[170:173], off offset:64
	v_cvt_pk_bf16_f32 v10, v94, v95
	v_cvt_pk_bf16_f32 v11, v96, v97
	v_cvt_pk_bf16_f32 v12, v82, v83
	v_cvt_pk_bf16_f32 v13, v84, v85
	v_cvt_pk_bf16_f32 v162, v78, v79
	v_cvt_pk_bf16_f32 v163, v80, v81
	v_cvt_pk_bf16_f32 v164, v70, v71
	v_cvt_pk_bf16_f32 v165, v72, v73
	v_or_b32_e32 v2, 64, v8
	v_mad_i64_i32 v[2:3], s[10:11], v2, s33, v[0:1]
	v_lshl_add_u64 v[2:3], v[2:3], 0, v[6:7]
	s_nop 1
	v_permlane16_swap_b32 v10, v12
	v_permlane16_swap_b32 v11, v13
	v_permlane16_swap_b32 v162, v164
	v_permlane16_swap_b32 v163, v165
	s_nop 1
	global_store_dwordx4 v[2:3], v[10:13], off
	global_store_dwordx4 v[2:3], v[162:165], off offset:64
	v_cvt_pk_bf16_f32 v166, v66, v67
	v_cvt_pk_bf16_f32 v167, v68, v69
	v_cvt_pk_bf16_f32 v168, v62, v63
	v_cvt_pk_bf16_f32 v169, v64, v65
	v_cvt_pk_bf16_f32 v170, v46, v47
	v_cvt_pk_bf16_f32 v171, v48, v49
	v_cvt_pk_bf16_f32 v172, v42, v43
	v_cvt_pk_bf16_f32 v173, v44, v45
	v_or_b32_e32 v2, 0x50, v8
	v_mad_i64_i32 v[2:3], s[10:11], v2, s33, v[0:1]
	v_lshl_add_u64 v[2:3], v[2:3], 0, v[6:7]
	s_nop 1
	v_permlane16_swap_b32 v166, v168
	v_permlane16_swap_b32 v167, v169
	v_permlane16_swap_b32 v170, v172
	v_permlane16_swap_b32 v171, v173
	s_nop 1
	global_store_dwordx4 v[2:3], v[166:169], off
	global_store_dwordx4 v[2:3], v[170:173], off offset:64
	v_cvt_pk_bf16_f32 v10, v34, v35
	v_cvt_pk_bf16_f32 v11, v36, v37
	v_cvt_pk_bf16_f32 v12, v30, v31
	v_cvt_pk_bf16_f32 v13, v32, v33
	v_cvt_pk_bf16_f32 v162, v26, v27
	v_cvt_pk_bf16_f32 v163, v28, v29
	v_cvt_pk_bf16_f32 v164, v22, v23
	v_cvt_pk_bf16_f32 v165, v24, v25
	v_or_b32_e32 v2, 0x60, v8
	v_mad_i64_i32 v[2:3], s[10:11], v2, s33, v[0:1]
	v_lshl_add_u64 v[2:3], v[2:3], 0, v[6:7]
	s_nop 1
	v_permlane16_swap_b32 v10, v12
	v_permlane16_swap_b32 v11, v13
	v_permlane16_swap_b32 v162, v164
	v_permlane16_swap_b32 v163, v165
	s_nop 1
	global_store_dwordx4 v[2:3], v[10:13], off
	global_store_dwordx4 v[2:3], v[162:165], off offset:64
	v_cvt_pk_bf16_f32 v166, v18, v19
	v_cvt_pk_bf16_f32 v167, v20, v21
	v_cvt_pk_bf16_f32 v168, v98, v99
	v_cvt_pk_bf16_f32 v169, v100, v101
	v_cvt_pk_bf16_f32 v170, v90, v91
	v_cvt_pk_bf16_f32 v171, v92, v93
	v_cvt_pk_bf16_f32 v172, v74, v75
	v_cvt_pk_bf16_f32 v173, v76, v77
	v_or_b32_e32 v2, 0x70, v8
	v_mad_i64_i32 v[0:1], s[10:11], v2, s33, v[0:1]
	v_lshl_add_u64 v[0:1], v[0:1], 0, v[6:7]
	s_mov_b64 s[10:11], 0
	s_nop 1
	v_permlane16_swap_b32 v166, v168
	v_permlane16_swap_b32 v167, v169
	v_permlane16_swap_b32 v170, v172
	v_permlane16_swap_b32 v171, v173
	s_nop 1
	global_store_dwordx4 v[0:1], v[166:169], off
	global_store_dwordx4 v[0:1], v[170:173], off offset:64

.LBB0_955:
	v_or_b32_e32 v0, s34, v129
	v_and_b32_e32 v1, 64, v128
	v_add_u32_e32 v0, v0, v130
	v_lshlrev_b32_e32 v2, 2, v127
	v_or3_b32 v6, v2, v1, s25
	v_ashrrev_i32_e32 v1, 31, v0
	v_lshlrev_b64 v[2:3], 11, v[0:1]
	v_lshl_add_u64 v[2:3], s[6:7], 0, v[2:3]
	v_lshlrev_b32_e32 v6, 1, v6
	v_and_b32_e32 v9, 1, v127
	v_mul_u32_u24_e32 v9, 24, v9
	v_add_u32_e32 v6, v6, v9
	v_mov_b32_e32 v7, v17
	v_cvt_pk_bf16_f32 v160, v46, v47
	v_cvt_pk_bf16_f32 v161, v48, v49
	v_cvt_pk_bf16_f32 v162, v42, v43
	v_cvt_pk_bf16_f32 v163, v44, v45
	v_cvt_pk_bf16_f32 v164, v34, v35
	v_cvt_pk_bf16_f32 v165, v36, v37
	v_cvt_pk_bf16_f32 v166, v22, v23
	v_cvt_pk_bf16_f32 v167, v24, v25
	v_lshl_add_u64 v[2:3], v[2:3], 0, v[6:7]
	s_nop 1
	v_permlane16_swap_b32 v160, v162
	v_permlane16_swap_b32 v161, v163
	v_permlane16_swap_b32 v164, v166
	v_permlane16_swap_b32 v165, v167
	s_nop 1
	global_store_dwordx4 v[2:3], v[160:163], off
	global_store_dwordx4 v[2:3], v[164:167], off offset:64
	v_cvt_pk_bf16_f32 v168, v30, v31
	v_cvt_pk_bf16_f32 v169, v32, v33
	v_cvt_pk_bf16_f32 v170, v18, v19
	v_cvt_pk_bf16_f32 v171, v20, v21
	v_cvt_pk_bf16_f32 v172, v38, v39
	v_cvt_pk_bf16_f32 v173, v40, v41
	v_cvt_pk_bf16_f32 v174, v26, v27
	v_cvt_pk_bf16_f32 v175, v28, v29
	v_or_b32_e32 v2, 16, v0
	v_ashrrev_i32_e32 v3, 31, v2
	v_lshlrev_b64 v[2:3], 11, v[2:3]
	v_lshl_add_u64 v[2:3], s[6:7], 0, v[2:3]
	v_lshl_add_u64 v[2:3], v[2:3], 0, v[6:7]
	s_nop 1
	v_permlane16_swap_b32 v168, v170
	v_permlane16_swap_b32 v169, v171
	v_permlane16_swap_b32 v172, v174
	v_permlane16_swap_b32 v173, v175
	s_nop 1
	global_store_dwordx4 v[2:3], v[168:171], off
	global_store_dwordx4 v[2:3], v[172:175], off offset:64
	v_cvt_pk_bf16_f32 v160, v70, v71
	v_cvt_pk_bf16_f32 v161, v72, v73
	v_cvt_pk_bf16_f32 v162, v66, v67
	v_cvt_pk_bf16_f32 v163, v68, v69
	v_cvt_pk_bf16_f32 v164, v62, v63
	v_cvt_pk_bf16_f32 v165, v64, v65
	v_cvt_pk_bf16_f32 v166, v58, v59
	v_cvt_pk_bf16_f32 v167, v60, v61
	v_or_b32_e32 v2, 32, v0
	v_ashrrev_i32_e32 v3, 31, v2
	v_lshlrev_b64 v[2:3], 11, v[2:3]
	v_lshl_add_u64 v[2:3], s[6:7], 0, v[2:3]
	v_lshl_add_u64 v[2:3], v[2:3], 0, v[6:7]
	v_or_b32_e32 v0, 48, v0
	v_ashrrev_i32_e32 v1, 31, v0
	v_lshlrev_b64 v[0:1], 11, v[0:1]
	v_lshl_add_u64 v[0:1], s[6:7], 0, v[0:1]
	s_nop 1
	v_permlane16_swap_b32 v160, v162
	v_permlane16_swap_b32 v161, v163
	v_permlane16_swap_b32 v164, v166
	v_permlane16_swap_b32 v165, v167
	s_nop 1
	global_store_dwordx4 v[2:3], v[160:163], off
	global_store_dwordx4 v[2:3], v[164:167], off offset:64
	v_cvt_pk_bf16_f32 v168, v78, v79
	v_cvt_pk_bf16_f32 v169, v80, v81
	v_cvt_pk_bf16_f32 v170, v74, v75
	v_cvt_pk_bf16_f32 v171, v76, v77
	v_cvt_pk_bf16_f32 v172, v82, v83
	v_cvt_pk_bf16_f32 v173, v84, v85
	v_cvt_pk_bf16_f32 v174, v86, v87
	v_cvt_pk_bf16_f32 v175, v88, v89
	v_lshl_add_u64 v[0:1], v[0:1], 0, v[6:7]
	s_nop 1
	v_permlane16_swap_b32 v168, v170
	v_permlane16_swap_b32 v169, v171
	v_permlane16_swap_b32 v172, v174
	v_permlane16_swap_b32 v173, v175
	s_nop 1
	global_store_dwordx4 v[0:1], v[168:171], off
	global_store_dwordx4 v[0:1], v[172:175], off offset:64

.Lpfa_skip_m2:
	s_mov_b32 s99, 1
	v_or_b32_e32 v0, s43, v127
	v_and_b32_e32 v1, 64, v126
	v_add_u32_e32 v0, v0, v128
	v_lshlrev_b32_e32 v2, 2, v125
	v_or3_b32 v6, v2, v1, s34
	v_ashrrev_i32_e32 v1, 31, v0
	v_lshlrev_b64 v[2:3], 11, v[0:1]
	v_lshl_add_u64 v[2:3], s[6:7], 0, v[2:3]
	v_lshlrev_b32_e32 v6, 1, v6
	v_and_b32_e32 v9, 1, v125
	v_mul_u32_u24_e32 v9, 24, v9
	v_add_u32_e32 v6, v6, v9
	v_mov_b32_e32 v7, v17
	v_cvt_pk_bf16_f32 v160, v86, v87
	v_cvt_pk_bf16_f32 v161, v88, v89
	v_cvt_pk_bf16_f32 v162, v82, v83
	v_cvt_pk_bf16_f32 v163, v84, v85
	v_cvt_pk_bf16_f32 v164, v74, v75
	v_cvt_pk_bf16_f32 v165, v76, v77
	v_cvt_pk_bf16_f32 v166, v66, v67
	v_cvt_pk_bf16_f32 v167, v68, v69
	v_lshl_add_u64 v[2:3], v[2:3], 0, v[6:7]
	s_nop 1
	v_permlane16_swap_b32 v160, v162
	v_permlane16_swap_b32 v161, v163
	v_permlane16_swap_b32 v164, v166
	v_permlane16_swap_b32 v165, v167
	s_nop 1
	global_store_dwordx4 v[2:3], v[160:163], off
	global_store_dwordx4 v[2:3], v[164:167], off offset:64
	v_cvt_pk_bf16_f32 v168, v54, v55
	v_cvt_pk_bf16_f32 v169, v56, v57
	v_cvt_pk_bf16_f32 v170, v46, v47
	v_cvt_pk_bf16_f32 v171, v48, v49
	v_cvt_pk_bf16_f32 v172, v38, v39
	v_cvt_pk_bf16_f32 v173, v40, v41
	v_cvt_pk_bf16_f32 v174, v34, v35
	v_cvt_pk_bf16_f32 v175, v36, v37
	v_or_b32_e32 v2, 16, v0
	v_ashrrev_i32_e32 v3, 31, v2
	v_lshlrev_b64 v[2:3], 11, v[2:3]
	v_lshl_add_u64 v[2:3], s[6:7], 0, v[2:3]
	v_lshl_add_u64 v[2:3], v[2:3], 0, v[6:7]
	s_nop 1
	v_permlane16_swap_b32 v168, v170
	v_permlane16_swap_b32 v169, v171
	v_permlane16_swap_b32 v172, v174
	v_permlane16_swap_b32 v173, v175
	s_nop 1
	global_store_dwordx4 v[2:3], v[168:171], off
	global_store_dwordx4 v[2:3], v[172:175], off offset:64
	v_cvt_pk_bf16_f32 v160, v70, v71
	v_cvt_pk_bf16_f32 v161, v72, v73
	v_cvt_pk_bf16_f32 v162, v62, v63
	v_cvt_pk_bf16_f32 v163, v64, v65
	v_cvt_pk_bf16_f32 v164, v50, v51
	v_cvt_pk_bf16_f32 v165, v52, v53
	v_cvt_pk_bf16_f32 v166, v42, v43
	v_cvt_pk_bf16_f32 v167, v44, v45
	v_or_b32_e32 v2, 32, v0
	v_ashrrev_i32_e32 v3, 31, v2
	v_lshlrev_b64 v[2:3], 11, v[2:3]
	v_lshl_add_u64 v[2:3], s[6:7], 0, v[2:3]
	v_lshl_add_u64 v[2:3], v[2:3], 0, v[6:7]
	v_or_b32_e32 v0, 48, v0
	v_ashrrev_i32_e32 v1, 31, v0
	v_lshlrev_b64 v[0:1], 11, v[0:1]
	v_lshl_add_u64 v[0:1], s[6:7], 0, v[0:1]
	s_nop 1
	v_permlane16_swap_b32 v160, v162
	v_permlane16_swap_b32 v161, v163
	v_permlane16_swap_b32 v164, v166
	v_permlane16_swap_b32 v165, v167
	s_nop 1
	global_store_dwordx4 v[2:3], v[160:163], off
	global_store_dwordx4 v[2:3], v[164:167], off offset:64
	v_cvt_pk_bf16_f32 v168, v26, v27
	v_cvt_pk_bf16_f32 v169, v28, v29
	v_cvt_pk_bf16_f32 v170, v30, v31
	v_cvt_pk_bf16_f32 v171, v32, v33
	v_cvt_pk_bf16_f32 v172, v78, v79
	v_cvt_pk_bf16_f32 v173, v80, v81
	v_cvt_pk_bf16_f32 v174, v58, v59
	v_cvt_pk_bf16_f32 v175, v60, v61
	v_lshl_add_u64 v[0:1], v[0:1], 0, v[6:7]
	s_nop 1
	v_permlane16_swap_b32 v168, v170
	v_permlane16_swap_b32 v169, v171
	v_permlane16_swap_b32 v172, v174
	v_permlane16_swap_b32 v173, v175
	s_nop 1
	global_store_dwordx4 v[0:1], v[168:171], off
	global_store_dwordx4 v[0:1], v[172:175], off offset:64
